# attention A: four-slot V-fragment ring (spare register quad per step parity) with four fragments prefetched across the barrier
# baseline (speedup 1.0000x reference)
; #define FLAS __attribute__((address_space(3)))
; __device__ __forceinline__ void attn_unit_a(FLAS unsigned char* lds, const Unit u) {
;     ...
;     f32x16 pa0, pa1, pb0, pb1; float cbC = 0.f;
;     { bool zi; FA_BIAS(0, pa0, pa1, cbC, zi); if (zi) { pa0 = z16; pa1 = z16; }
;       const FLAS unsigned char* kb = lds + LA_K;
; #pragma unroll
;       for (int d0 = 0; d0 < 4; ++d0) { const int ko = (2 * d0 + hi) * 1024 + ((r32 ^ (2 * d0 + hi)) * 16); const bf16x8 a0 = *(const FLAS bf16x8*)(kb + ko), a1 = *(const FLAS bf16x8*)(kb + ko + 512);
;           pa0 = __builtin_amdgcn_mfma_f32_32x32x16_bf16(a0, qr[d0], pa0, 0, 0, 0); pa1 = __builtin_amdgcn_mfma_f32_32x32x16_bf16(a1, qr[d0], pa1, 0, 0, 0); } }
;     u32x4 pwa[4] = {{0u,0u,0u,0u},{0u,0u,0u,0u},{0u,0u,0u,0u},{0u,0u,0u,0u}}, pwb[4] = {{0u,0u,0u,0u},{0u,0u,0u,0u},{0u,0u,0u,0u},{0u,0u,0u,0u}};
;     auto step = [&](const int i, f32x16& pC0, f32x16& pC1, f32x16& pN0, f32x16& pN1, u32x4 (&PWC)[4], u32x4 (&PWN)[4]) __attribute__((always_inline)) {
;         if (pend) {
; #pragma unroll
;             for (int d = 0; d < NDB; ++d) o[d] = o[d] * fpend;
;             pend = false; }
;         if (i + 2 < NT) { kreg = *(const u32x4*)(ksrc + (size_t)(u.t_lo + i + 2) * 64 * u.ldk);
; #pragma unroll
;             for (int j = 0; j < 2; ++j) vreg[j] = *(const u32x4*)(vsrc + (size_t)j * 64 * MTOK + (u.t_lo + i + 2) * 64); }
;         const int vsp = (i == 0) ? 0 : ((i - 1) & 3);
;         const FLAS unsigned char* vb_ = lds + LA_V + vsp * VBUF + r32 * VPITCH + hi * 16;
;         const FLAS unsigned char* kb = lds + LA_K + ((i + 1) & 1) * KBUF;
;     ...
;         u32x4 vr[3];
; #pragma unroll
;         for (int m = 0; m < 3; ++m) vr[m] = FA_VFRAG(m);
;         const float off = cbC - mrun;
.Lprio_skip:
	s_waitcnt lgkmcnt(0)
	v_readlane_b32 s100, v254, 47
	v_mov_b32_e32 v92, s13
	s_nop 3
	v_mov_b32_e32 v93, s100
	ds_read_b32 v92, v92
	ds_read_b32 v93, v93
	v_sub_f32_e32 v94, v204, v211
	v_add_f32_e32 v96, v128, v94
	v_add_f32_e32 v112, v144, v94
	v_add_f32_e32 v97, v129, v94
	v_add_f32_e32 v113, v145, v94
	v_add_f32_e32 v98, v130, v94
	v_add_f32_e32 v114, v146, v94
	v_add_f32_e32 v99, v131, v94
	v_add_f32_e32 v115, v147, v94
	v_add_f32_e32 v100, v132, v94
	v_add_f32_e32 v116, v148, v94
	v_add_f32_e32 v101, v133, v94
	v_add_f32_e32 v117, v149, v94
	v_add_f32_e32 v102, v134, v94
	v_add_f32_e32 v118, v150, v94
	v_add_f32_e32 v103, v135, v94
	v_add_f32_e32 v119, v151, v94
	v_add_f32_e32 v104, v136, v94
	v_add_f32_e32 v120, v152, v94
	v_add_f32_e32 v105, v137, v94
	v_add_f32_e32 v121, v153, v94
	v_add_f32_e32 v106, v138, v94
	v_add_f32_e32 v122, v154, v94
	v_add_f32_e32 v107, v139, v94
	v_add_f32_e32 v123, v155, v94
	v_add_f32_e32 v108, v140, v94
	v_add_f32_e32 v124, v156, v94
	v_add_f32_e32 v109, v141, v94
	v_add_f32_e32 v125, v157, v94
	v_add_f32_e32 v110, v142, v94
	v_add_f32_e32 v126, v158, v94
	v_add_f32_e32 v111, v143, v94
	v_add_f32_e32 v127, v159, v94
	v_mov_b32_e32 v144, 0x7fc00000
	v_mov_b32_e32 v145, 0x7fc00000
	v_mov_b32_e32 v146, 0x7fc00000
	v_mov_b32_e32 v147, 0x7fc00000
	v_mov_b32_e32 v148, 0x7fc00000
	v_mov_b32_e32 v149, 0x7fc00000
	v_mov_b32_e32 v150, 0x7fc00000
	v_mov_b32_e32 v151, 0x7fc00000
	v_mov_b32_e32 v152, 0x7fc00000
	v_mov_b32_e32 v153, 0x7fc00000
	v_mov_b32_e32 v154, 0x7fc00000
	v_mov_b32_e32 v155, 0x7fc00000
	v_mov_b32_e32 v156, 0x7fc00000
	v_mov_b32_e32 v157, 0x7fc00000
	v_mov_b32_e32 v158, 0x7fc00000
	v_mov_b32_e32 v159, 0x7fc00000
	v_mov_b32_e32 v204, 0
	v_mov_b32_e32 v205, 0
	v_mov_b32_e32 v206, 0
	v_mov_b32_e32 v207, 0
	s_waitcnt lgkmcnt(0)
	v_readfirstlane_b32 s101, v92
	v_readfirstlane_b32 s100, v93
	v_mov_b32_e32 v72, 0
	v_mov_b32_e32 v73, 0
	v_mov_b32_e32 v74, 0
	v_mov_b32_e32 v75, 0
	v_mov_b32_e32 v76, 0
	v_mov_b32_e32 v77, 0
	v_mov_b32_e32 v78, 0
	v_mov_b32_e32 v79, 0
	v_mov_b32_e32 v80, 0
	v_mov_b32_e32 v81, 0
	v_mov_b32_e32 v82, 0
	v_mov_b32_e32 v83, 0
	v_mov_b32_e32 v84, 0
	v_mov_b32_e32 v85, 0
	v_mov_b32_e32 v86, 0
	v_mov_b32_e32 v87, 0
	v_mov_b32_e32 v88, 0
	v_mov_b32_e32 v89, 0
	v_mov_b32_e32 v90, 0
	v_mov_b32_e32 v91, 0
	v_mov_b32_e32 v92, 0
	v_mov_b32_e32 v93, 0
	v_mov_b32_e32 v94, 0
	v_mov_b32_e32 v95, 0
	v_writelane_b32 v255, s50, 30
	v_writelane_b32 v255, s51, 31
	v_writelane_b32 v255, s52, 32
	v_writelane_b32 v255, s53, 33
	v_readfirstlane_b32 s50, v230
	v_readfirstlane_b32 s51, v231
	v_readfirstlane_b32 s52, v228
	v_readfirstlane_b32 s53, v229
	s_nop 3
	v_subrev_u32_e32 v230, s50, v230
	v_subrev_u32_e32 v228, s52, v228
	v_add_u32_e32 v230, v230, v208
	v_add_u32_e32 v228, v228, v208
	v_add_u32_e32 v231, 0x30000, v230
	v_add_u32_e32 v229, 0x400000, v228
	s_add_u32 s50, s50, 0xd660000
	s_addc_u32 s51, s51, 0
	s_add_u32 s52, s52, 0x13600000
	s_addc_u32 s53, s53, 0
	s_mov_b32 s99, 0x7fc00000
	s_add_i32 s12, s19, -1
	s_and_b32 s18, s12, 3
	s_mulk_i32 s18, 0x4800
	s_cmp_lg_u32 s49, 0
	s_cselect_b32 s12, s18, 0
	v_add_u32_e32 v200, s12, v251
	ds_read_b128 v[128:131], v200 offset:16384
	ds_read_b128 v[132:135], v200 offset:20992
	ds_read_b128 v[136:139], v200 offset:25600
	ds_read_b128 v[232:235], v200 offset:30208
	s_cbranch_execnz .LBB0_435
	s_branch .LBB0_434

; #define FLAS __attribute__((address_space(3)))
; __device__ __forceinline__ void attn_unit_a(FLAS unsigned char* lds, const Unit u) {
;     ...
;         if (i + 2 < NT) { kreg = *(const u32x4*)(ksrc + (size_t)(u.t_lo + i + 2) * 64 * u.ldk);
; #pragma unroll
;             for (int j = 0; j < 2; ++j) vreg[j] = *(const u32x4*)(vsrc + (size_t)j * 64 * MTOK + (u.t_lo + i + 2) * 64); }
;         const int vsp = (i == 0) ? 0 : ((i - 1) & 3);
;         const FLAS unsigned char* vb_ = lds + LA_V + vsp * VBUF + r32 * VPITCH + hi * 16;
;         const FLAS unsigned char* kb = lds + LA_K + ((i + 1) & 1) * KBUF;
;     ...
;         u32x4 vr[3];
; #pragma unroll
;         for (int m = 0; m < 3; ++m) vr[m] = FA_VFRAG(m);
;         const float off = cbC - mrun;
;         FA_SB();
;         float ra, rb, rm;
;         FA_PVM(0); pC0[0] = fadd_s(pC0[0], off); pC1[0] = fadd_s(pC1[0], off); pC0[1] = fadd_s(pC0[1], off); pC1[1] = fadd_s(pC1[1], off); pC0[2] = fadd_s(pC0[2], off); pC1[2] = fadd_s(pC1[2], off); FA_SB();
;         FA_PVM(1); ra = __builtin_fmaxf(__builtin_fmaxf(pC0[0], pC0[1]), pC0[2]); rb = __builtin_fmaxf(__builtin_fmaxf(pC1[0], pC1[1]), pC1[2]); pC0[3] = fadd_s(pC0[3], off); pC1[3] = fadd_s(pC1[3], off); pC0[4] = fadd_s(pC0[4], off); pC1[4] = fadd_s(pC1[4], off); FA_SB();
;         FA_PVM(2); ra = __builtin_fmaxf(__builtin_fmaxf(ra, pC0[3]), pC0[4]); rb = __builtin_fmaxf(__builtin_fmaxf(rb, pC1[3]), pC1[4]); pC0[5] = fadd_s(pC0[5], off); pC1[5] = fadd_s(pC1[5], off); pC0[6] = fadd_s(pC0[6], off); pC1[6] = fadd_s(pC1[6], off); FA_SB();
;         FA_PVM(3); ra = __builtin_fmaxf(__builtin_fmaxf(ra, pC0[5]), pC0[6]); rb = __builtin_fmaxf(__builtin_fmaxf(rb, pC1[5]), pC1[6]); pC0[7] = fadd_s(pC0[7], off); pC1[7] = fadd_s(pC1[7], off); pC0[8] = fadd_s(pC0[8], off); pC1[8] = fadd_s(pC1[8], off); FA_SB();
;         FA_PVM(4); ra = __builtin_fmaxf(__builtin_fmaxf(ra, pC0[7]), pC0[8]); rb = __builtin_fmaxf(__builtin_fmaxf(rb, pC1[7]), pC1[8]); pC0[9] = fadd_s(pC0[9], off); pC1[9] = fadd_s(pC1[9], off); pC0[10] = fadd_s(pC0[10], off); pC1[10] = fadd_s(pC1[10], off); FA_SB();
;         FA_PVM(5); ra = __builtin_fmaxf(__builtin_fmaxf(ra, pC0[9]), pC0[10]); rb = __builtin_fmaxf(__builtin_fmaxf(rb, pC1[9]), pC1[10]); pC0[11] = fadd_s(pC0[11], off); pC1[11] = fadd_s(pC1[11], off); pC0[12] = fadd_s(pC0[12], off); pC1[12] = fadd_s(pC1[12], off); FA_SB();
.LBB0_435:
	s_cmpk_lt_u32 s19, 0x7e
	s_cselect_b64 s[0:1], -1, 0
	s_cmpk_gt_u32 s19, 0x7d
	s_cselect_b64 s[4:5], -1, 0
	s_xor_b64 s[20:21], s[24:25], -1
	s_waitcnt lgkmcnt(2)
	v_mfma_f32_32x32x16_bf16 v[48:63], v[128:131], v[204:207], v[48:63]
	ds_read_b128 v[128:131], v200 offset:16416
	s_and_b64 vcc, exec, s[4:5]
	s_cbranch_vccnz .LBB0_437
	global_load_dwordx4 v[176:179], v230, s[50:51]
	global_load_dwordx4 v[180:183], v228, s[52:53] offset:256
	global_load_dwordx4 v[184:187], v229, s[52:53] offset:256
.LBB0_437:
	v_max3_f32 v140, v96, v97, v98
	v_max3_f32 v141, v112, v113, v114
	v_cvt_pk_bf16_f32 v196, v72, v73
	v_cvt_pk_bf16_f32 v197, v74, v75
	v_add_f32_e32 v212, v80, v212
	v_add_f32_e32 v212, v81, v212
	v_mfma_f32_32x32x16_bf16 v[32:47], v[132:135], v[204:207], v[32:47]
	ds_read_b128 v[132:135], v200 offset:21024
	v_max3_f32 v140, v140, v99, v100
	v_max3_f32 v141, v141, v115, v116
	v_cvt_pk_bf16_f32 v198, v76, v77
	v_cvt_pk_bf16_f32 v199, v78, v79
	v_add_f32_e32 v212, v82, v212
	v_add_f32_e32 v212, v83, v212
	s_waitcnt lgkmcnt(2)
	v_mfma_f32_32x32x16_bf16 v[16:31], v[136:139], v[204:207], v[16:31]
	ds_read_b128 v[136:139], v200 offset:25632
	v_max3_f32 v140, v140, v101, v102
	v_max3_f32 v141, v141, v117, v118
	v_cvt_pk_bf16_f32 v192, v80, v81
	v_cvt_pk_bf16_f32 v193, v82, v83
	v_add_f32_e32 v212, v84, v212
	v_add_f32_e32 v212, v85, v212
	v_mfma_f32_32x32x16_bf16 v[0:15], v[232:235], v[204:207], v[0:15]
	ds_read_b128 v[232:235], v200 offset:30240
	v_max3_f32 v140, v140, v103, v104
	v_max3_f32 v141, v141, v119, v120
	v_cvt_pk_bf16_f32 v194, v84, v85
	v_cvt_pk_bf16_f32 v195, v86, v87
	v_add_f32_e32 v212, v86, v212
	v_add_f32_e32 v212, v87, v212
	s_waitcnt lgkmcnt(2)
	v_mfma_f32_32x32x16_bf16 v[48:63], v[128:131], v[196:199], v[48:63]
	ds_read_b128 v[128:131], v200 offset:16448
	v_max3_f32 v140, v140, v105, v106
	v_max3_f32 v141, v141, v121, v122
	v_cvt_pk_bf16_f32 v188, v88, v89
	v_cvt_pk_bf16_f32 v189, v90, v91
	v_add_f32_e32 v212, v88, v212
	v_add_f32_e32 v212, v89, v212
	v_mfma_f32_32x32x16_bf16 v[32:47], v[132:135], v[196:199], v[32:47]
	ds_read_b128 v[132:135], v200 offset:21056
	v_max3_f32 v140, v140, v107, v108
	v_max3_f32 v141, v141, v123, v124
	v_cvt_pk_bf16_f32 v190, v92, v93
	v_cvt_pk_bf16_f32 v191, v94, v95
	v_add_f32_e32 v212, v90, v212
	v_add_f32_e32 v212, v91, v212
	s_waitcnt lgkmcnt(2)
	v_mfma_f32_32x32x16_bf16 v[16:31], v[136:139], v[196:199], v[16:31]
	ds_read_b128 v[136:139], v200 offset:25664
	v_max3_f32 v140, v140, v109, v110
	v_max3_f32 v141, v141, v125, v126
	v_add_f32_e32 v212, v92, v212
	v_add_f32_e32 v212, v93, v212
	v_mfma_f32_32x32x16_bf16 v[0:15], v[232:235], v[196:199], v[0:15]
	ds_read_b128 v[232:235], v200 offset:30272
	v_max3_f32 v140, v140, v141, v111
	v_max_f32_e32 v140, v140, v127
	v_add_f32_e32 v212, v94, v212
	v_add_f32_e32 v212, v95, v212
	s_andn2_b64 vcc, exec, s[20:21]
	s_cbranch_vccnz .LBB0_440
	v_cmp_lt_f32_e32 vcc, s39, v140
	s_cbranch_vccnz .Lresc_e
	s_mov_b64 s[20:21], 0
.LBB0_442:
	s_waitcnt lgkmcnt(2)
	v_mfma_f32_32x32x16_bf16 v[48:63], v[128:131], v[192:195], v[48:63]
	ds_read_b128 v[128:131], v200 offset:16480
	v_exp_f32_e32 v96, v96
	v_exp_f32_e32 v97, v97
	v_mfma_f32_32x32x16_bf16 v[32:47], v[132:135], v[192:195], v[32:47]
	ds_read_b128 v[132:135], v200 offset:21088
	v_exp_f32_e32 v98, v98
	v_exp_f32_e32 v99, v99
	v_add_f32_e32 v212, v96, v212
	v_add_f32_e32 v212, v97, v212
	s_waitcnt lgkmcnt(2)
	v_mfma_f32_32x32x16_bf16 v[16:31], v[136:139], v[192:195], v[16:31]
	ds_read_b128 v[136:139], v200 offset:25696
	v_exp_f32_e32 v100, v100
	v_exp_f32_e32 v101, v101
	v_add_f32_e32 v212, v98, v212
	v_add_f32_e32 v212, v99, v212
	v_mfma_f32_32x32x16_bf16 v[0:15], v[232:235], v[192:195], v[0:15]
	ds_read_b128 v[232:235], v200 offset:30304
	v_exp_f32_e32 v102, v102
	v_exp_f32_e32 v103, v103
	v_add_f32_e32 v212, v100, v212
	v_add_f32_e32 v212, v101, v212
	s_waitcnt lgkmcnt(2)
	v_mfma_f32_32x32x16_bf16 v[48:63], v[128:131], v[188:191], v[48:63]
	ds_read_b128 v[204:207], v247 offset:8192
	ds_read_b128 v[200:203], v247 offset:8704
	ds_read_b128 v[196:199], v248 offset:8192
	ds_read_b128 v[192:195], v248 offset:8704
	v_exp_f32_e32 v104, v104
	v_exp_f32_e32 v105, v105
	v_add_f32_e32 v212, v102, v212
	v_add_f32_e32 v212, v103, v212
	v_mfma_f32_32x32x16_bf16 v[32:47], v[132:135], v[188:191], v[32:47]
	v_exp_f32_e32 v106, v106
	v_exp_f32_e32 v107, v107
	v_add_f32_e32 v212, v104, v212
	v_add_f32_e32 v212, v105, v212
	s_waitcnt lgkmcnt(4)
	v_mfma_f32_32x32x16_bf16 v[16:31], v[136:139], v[188:191], v[16:31]
	v_exp_f32_e32 v108, v108
	v_exp_f32_e32 v109, v109
	v_add_f32_e32 v212, v106, v212
	v_add_f32_e32 v212, v107, v212
	v_mfma_f32_32x32x16_bf16 v[0:15], v[232:235], v[188:191], v[0:15]
	v_exp_f32_e32 v110, v110
	v_exp_f32_e32 v111, v111
	v_add_f32_e32 v212, v108, v212
	v_add_f32_e32 v212, v109, v212
	s_sub_i32 s12, s48, 31
	s_cmpk_lt_i32 s12, 0x22f
	s_cselect_b32 s98, s100, s101
	s_cselect_b32 s15, 1, 0
	s_cmpk_gt_i32 s48, 0xfd92
	s_cselect_b32 s15, s15, 0
	s_cmp_lg_u32 s15, 0
	s_cbranch_scc1 .Lgather_e
	s_cmp_lg_u32 s99, s98
	s_cbranch_scc1 .Lz_upd_e

; #define FLAS __attribute__((address_space(3)))
; #define FA_SB() __builtin_amdgcn_sched_barrier(0)
; #define FA_EXP2(J, PX, R) do { const float e0_ = __builtin_amdgcn_exp2f(PX[R]), e1_ = __builtin_amdgcn_exp2f(PX[(R) + 1]); ps += e0_; ps += e1_; PWN[(J) >> 2][(J) & 3] = cvtpk(e0_, e1_); } while (0)
; __device__ __forceinline__ void attn_unit_a(FLAS unsigned char* lds, const Unit u) {
;     ...
;         u32x4 vr[3];
; #pragma unroll
;         for (int m = 0; m < 3; ++m) vr[m] = FA_VFRAG(m);
;     ...
;         kf[0] = FA_KF(2, 0); kf[1] = FA_KF(2, 1); FA_EXP2(9, pC1, 2); FA_SB();
;         pN0 = __builtin_amdgcn_mfma_f32_32x32x16_bf16(kf[2], qr[1], pN0, 0, 0, 0); FA_EXP2(10, pC1, 4); FA_SB();
;         pN1 = __builtin_amdgcn_mfma_f32_32x32x16_bf16(kf[3], qr[1], pN1, 0, 0, 0); kf[2] = FA_KF(3, 0); kf[3] = FA_KF(3, 1); FA_EXP2(11, pC1, 6); FA_SB();
;         pN0 = __builtin_amdgcn_mfma_f32_32x32x16_bf16(kf[0], qr[2], pN0, 0, 0, 0); FA_EXP2(12, pC1, 8); FA_SB();
;         pN1 = __builtin_amdgcn_mfma_f32_32x32x16_bf16(kf[1], qr[2], pN1, 0, 0, 0); FA_EXP2(13, pC1, 10); FA_SB();
;         pN0 = __builtin_amdgcn_mfma_f32_32x32x16_bf16(kf[2], qr[3], pN0, 0, 0, 0); FA_EXP2(14, pC1, 12); FA_SB();
;         pN1 = __builtin_amdgcn_mfma_f32_32x32x16_bf16(kf[3], qr[3], pN1, 0, 0, 0); FA_EXP2(15, pC1, 14); FA_SB();
;     ...
;         lsum += ps; cbC = cbN;
;         if (i + 2 < NT) { *(FLAS u32x4*)(lds + LA_K + (i & 1) * KBUF + kdst) = kreg;
; #pragma unroll
;             for (int j = 0; j < 2; ++j) { *(FLAS u32x2*)(lds + LA_V + ((i + 2) & 3) * VBUF + vdst + j * 64 * VPITCH) = (u32x2){vreg[j].x, vreg[j].y}; *(FLAS u32x2*)(lds + LA_V + ((i + 2) & 3) * VBUF + vdst + j * 64 * VPITCH + 16) = (u32x2){vreg[j].z, vreg[j].w}; } }
.Lk2_e:
	ds_read_b128 v[128:131], v249 offset:8192
	ds_read_b128 v[132:135], v249 offset:8704
	s_add_i32 s34, s19, 2
	v_mfma_f32_32x32x16_bf16 v[64:79], v[196:199], v[164:167], v[64:79]
	v_exp_f32_e32 v116, v116
	v_exp_f32_e32 v117, v117
	v_mfma_f32_32x32x16_bf16 v[80:95], v[192:195], v[164:167], v[80:95]
	ds_read_b128 v[136:139], v250 offset:8192
	ds_read_b128 v[140:143], v250 offset:8704
	s_and_b32 s0, s34, 2
	s_mulk_i32 s0, 0x4800
	v_add_u32_e32 v188, s0, v245
	v_add_u32_e32 v189, 0x4000, v188
	v_add_u32_e32 v188, 0x6000, v188
	s_waitcnt vmcnt(2)
	ds_write_b128 v225, v[176:179]
	s_waitcnt vmcnt(1)
	ds_write2_b64 v189, v[180:181], v[182:183] offset1:2
	s_waitcnt vmcnt(0)
	ds_write2_b64 v188, v[184:185], v[186:187] offset0:128 offset1:130
	v_exp_f32_e32 v118, v118
	v_exp_f32_e32 v119, v119
	s_and_b32 s0, s19, 2
	s_mulk_i32 s0, 0x4800
	v_add_u32_e32 v201, s0, v251
	ds_read_b128 v[204:207], v201 offset:30208
	s_waitcnt lgkmcnt(6)
	v_mfma_f32_32x32x16_bf16 v[64:79], v[128:131], v[168:171], v[64:79]
	ds_read_b128 v[128:131], v201 offset:16384
	v_exp_f32_e32 v120, v120
	v_exp_f32_e32 v121, v121
	v_mfma_f32_32x32x16_bf16 v[80:95], v[132:135], v[168:171], v[80:95]
	ds_read_b128 v[132:135], v201 offset:20992
	v_exp_f32_e32 v122, v122
	v_exp_f32_e32 v123, v123
	s_waitcnt lgkmcnt(6)
	v_mfma_f32_32x32x16_bf16 v[64:79], v[136:139], v[172:175], v[64:79]
	ds_read_b128 v[136:139], v201 offset:25600
	v_exp_f32_e32 v124, v124
	v_exp_f32_e32 v125, v125
	v_mfma_f32_32x32x16_bf16 v[80:95], v[140:143], v[172:175], v[80:95]
	v_exp_f32_e32 v126, v126
	v_exp_f32_e32 v127, v127
	v_cvt_pk_bf16_f32 v140, v96, v97
	v_cvt_pk_bf16_f32 v141, v98, v99
	v_cvt_pk_bf16_f32 v142, v100, v101
	v_cvt_pk_bf16_f32 v143, v102, v103

; #define FLAS __attribute__((address_space(3)))
; __device__ __forceinline__ void attn_unit_a(FLAS unsigned char* lds, const Unit u) {
;     ...
;         if (i + 2 < NT) { kreg = *(const u32x4*)(ksrc + (size_t)(u.t_lo + i + 2) * 64 * u.ldk);
; #pragma unroll
;             for (int j = 0; j < 2; ++j) vreg[j] = *(const u32x4*)(vsrc + (size_t)j * 64 * MTOK + (u.t_lo + i + 2) * 64); }
;         const int vsp = (i == 0) ? 0 : ((i - 1) & 3);
;         const FLAS unsigned char* vb_ = lds + LA_V + vsp * VBUF + r32 * VPITCH + hi * 16;
;         const FLAS unsigned char* kb = lds + LA_K + ((i + 1) & 1) * KBUF;
;     ...
;         u32x4 vr[3];
; #pragma unroll
;         for (int m = 0; m < 3; ++m) vr[m] = FA_VFRAG(m);
;         const float off = cbC - mrun;
;         FA_SB();
;         float ra, rb, rm;
;         FA_PVM(0); pC0[0] = fadd_s(pC0[0], off); pC1[0] = fadd_s(pC1[0], off); pC0[1] = fadd_s(pC0[1], off); pC1[1] = fadd_s(pC1[1], off); pC0[2] = fadd_s(pC0[2], off); pC1[2] = fadd_s(pC1[2], off); FA_SB();
;         FA_PVM(1); ra = __builtin_fmaxf(__builtin_fmaxf(pC0[0], pC0[1]), pC0[2]); rb = __builtin_fmaxf(__builtin_fmaxf(pC1[0], pC1[1]), pC1[2]); pC0[3] = fadd_s(pC0[3], off); pC1[3] = fadd_s(pC1[3], off); pC0[4] = fadd_s(pC0[4], off); pC1[4] = fadd_s(pC1[4], off); FA_SB();
;         FA_PVM(2); ra = __builtin_fmaxf(__builtin_fmaxf(ra, pC0[3]), pC0[4]); rb = __builtin_fmaxf(__builtin_fmaxf(rb, pC1[3]), pC1[4]); pC0[5] = fadd_s(pC0[5], off); pC1[5] = fadd_s(pC1[5], off); pC0[6] = fadd_s(pC0[6], off); pC1[6] = fadd_s(pC1[6], off); FA_SB();
;         FA_PVM(3); ra = __builtin_fmaxf(__builtin_fmaxf(ra, pC0[5]), pC0[6]); rb = __builtin_fmaxf(__builtin_fmaxf(rb, pC1[5]), pC1[6]); pC0[7] = fadd_s(pC0[7], off); pC1[7] = fadd_s(pC1[7], off); pC0[8] = fadd_s(pC0[8], off); pC1[8] = fadd_s(pC1[8], off); FA_SB();
;         FA_PVM(4); ra = __builtin_fmaxf(__builtin_fmaxf(ra, pC0[7]), pC0[8]); rb = __builtin_fmaxf(__builtin_fmaxf(rb, pC1[7]), pC1[8]); pC0[9] = fadd_s(pC0[9], off); pC1[9] = fadd_s(pC1[9], off); pC0[10] = fadd_s(pC0[10], off); pC1[10] = fadd_s(pC1[10], off); FA_SB();
;         FA_PVM(5); ra = __builtin_fmaxf(__builtin_fmaxf(ra, pC0[9]), pC0[10]); rb = __builtin_fmaxf(__builtin_fmaxf(rb, pC1[9]), pC1[10]); pC0[11] = fadd_s(pC0[11], off); pC1[11] = fadd_s(pC1[11], off); pC0[12] = fadd_s(pC0[12], off); pC1[12] = fadd_s(pC1[12], off); FA_SB();
.LBB0_458:
	s_cmpk_lt_u32 s19, 0x7d
	s_cselect_b64 s[20:21], -1, 0
	s_waitcnt lgkmcnt(2)
	v_mfma_f32_32x32x16_bf16 v[48:63], v[128:131], v[140:143], v[48:63]
	ds_read_b128 v[128:131], v201 offset:16416
	s_cmpk_gt_u32 s19, 0x7c
	s_cbranch_scc1 .LBB0_460
	global_load_dwordx4 v[176:179], v231, s[50:51]
	global_load_dwordx4 v[180:183], v228, s[52:53] offset:384
	global_load_dwordx4 v[184:187], v229, s[52:53] offset:384
.LBB0_460:
	v_max3_f32 v96, v64, v65, v66
	v_max3_f32 v97, v80, v81, v82
	v_cvt_pk_bf16_f32 v232, v104, v105
	v_cvt_pk_bf16_f32 v233, v106, v107
	v_add_f32_e32 v212, v112, v212
	v_add_f32_e32 v212, v113, v212
	v_mfma_f32_32x32x16_bf16 v[32:47], v[132:135], v[140:143], v[32:47]
	ds_read_b128 v[132:135], v201 offset:21024
	v_max3_f32 v96, v96, v67, v68
	v_max3_f32 v97, v97, v83, v84
	v_cvt_pk_bf16_f32 v234, v108, v109
	v_cvt_pk_bf16_f32 v235, v110, v111
	v_add_f32_e32 v212, v114, v212
	v_add_f32_e32 v212, v115, v212
	s_waitcnt lgkmcnt(2)
	v_mfma_f32_32x32x16_bf16 v[16:31], v[136:139], v[140:143], v[16:31]
	ds_read_b128 v[136:139], v201 offset:25632
	v_max3_f32 v96, v96, v69, v70
	v_max3_f32 v97, v97, v85, v86
	v_add_f32_e32 v212, v116, v212
	v_add_f32_e32 v212, v117, v212
	v_mfma_f32_32x32x16_bf16 v[0:15], v[204:207], v[140:143], v[0:15]
	ds_read_b128 v[204:207], v201 offset:30240
	v_max3_f32 v96, v96, v71, v72
	v_max3_f32 v97, v97, v87, v88
	v_add_f32_e32 v212, v118, v212
	v_add_f32_e32 v212, v119, v212
	s_waitcnt lgkmcnt(2)
	v_mfma_f32_32x32x16_bf16 v[48:63], v[128:131], v[232:235], v[48:63]
	ds_read_b128 v[128:131], v201 offset:16448
	v_max3_f32 v96, v96, v73, v74
	v_max3_f32 v97, v97, v89, v90
	v_cvt_pk_bf16_f32 v140, v112, v113
	v_cvt_pk_bf16_f32 v141, v114, v115
	v_add_f32_e32 v212, v120, v212
	v_add_f32_e32 v212, v121, v212
	v_mfma_f32_32x32x16_bf16 v[32:47], v[132:135], v[232:235], v[32:47]
	ds_read_b128 v[132:135], v201 offset:21056
	v_max3_f32 v96, v96, v75, v76
	v_max3_f32 v97, v97, v91, v92
	v_cvt_pk_bf16_f32 v142, v116, v117
	v_cvt_pk_bf16_f32 v143, v118, v119
	v_add_f32_e32 v212, v122, v212
	v_add_f32_e32 v212, v123, v212
	s_waitcnt lgkmcnt(2)
	v_mfma_f32_32x32x16_bf16 v[16:31], v[136:139], v[232:235], v[16:31]
	ds_read_b128 v[136:139], v201 offset:25664
	v_max3_f32 v96, v96, v77, v78
	v_max3_f32 v97, v97, v93, v94
	v_add_f32_e32 v212, v124, v212
	v_add_f32_e32 v212, v125, v212
	v_mfma_f32_32x32x16_bf16 v[0:15], v[204:207], v[232:235], v[0:15]
	ds_read_b128 v[204:207], v201 offset:30272
	v_max3_f32 v96, v96, v97, v79
	v_max_f32_e32 v96, v96, v95
	v_add_f32_e32 v212, v126, v212
	v_add_f32_e32 v212, v127, v212
	v_cmp_lt_f32_e32 vcc, s39, v96
	s_mov_b64 s[0:1], 0
	s_cbranch_vccnz .Lresc_o
.LBB0_462:
	s_waitcnt lgkmcnt(2)
	v_mfma_f32_32x32x16_bf16 v[48:63], v[128:131], v[140:143], v[48:63]
	ds_read_b128 v[128:131], v201 offset:16480
	v_exp_f32_e32 v64, v64
	v_exp_f32_e32 v65, v65
	v_cvt_pk_bf16_f32 v232, v120, v121
	v_cvt_pk_bf16_f32 v233, v122, v123
	v_mfma_f32_32x32x16_bf16 v[32:47], v[132:135], v[140:143], v[32:47]
	ds_read_b128 v[132:135], v201 offset:21088
	v_exp_f32_e32 v66, v66
	v_exp_f32_e32 v67, v67
	v_add_f32_e32 v212, v64, v212
	v_add_f32_e32 v212, v65, v212
	v_cvt_pk_bf16_f32 v234, v124, v125
	v_cvt_pk_bf16_f32 v235, v126, v127
	s_waitcnt lgkmcnt(2)
	v_mfma_f32_32x32x16_bf16 v[16:31], v[136:139], v[140:143], v[16:31]
	ds_read_b128 v[136:139], v201 offset:25696
	v_exp_f32_e32 v68, v68
	v_exp_f32_e32 v69, v69
	v_add_f32_e32 v212, v66, v212
	v_add_f32_e32 v212, v67, v212
	v_mfma_f32_32x32x16_bf16 v[0:15], v[204:207], v[140:143], v[0:15]
	ds_read_b128 v[204:207], v201 offset:30304
	v_exp_f32_e32 v70, v70
	v_exp_f32_e32 v71, v71
	v_add_f32_e32 v212, v68, v212
	v_add_f32_e32 v212, v69, v212
	s_waitcnt lgkmcnt(2)
	v_mfma_f32_32x32x16_bf16 v[48:63], v[128:131], v[232:235], v[48:63]
	ds_read_b128 v[200:203], v247
	ds_read_b128 v[196:199], v247 offset:512
	ds_read_b128 v[192:195], v248
	ds_read_b128 v[188:191], v248 offset:512
	v_exp_f32_e32 v72, v72
	v_exp_f32_e32 v73, v73
	v_add_f32_e32 v212, v70, v212
	v_add_f32_e32 v212, v71, v212
	v_mfma_f32_32x32x16_bf16 v[32:47], v[132:135], v[232:235], v[32:47]
	v_exp_f32_e32 v74, v74
	v_exp_f32_e32 v75, v75
	v_add_f32_e32 v212, v72, v212
	v_add_f32_e32 v212, v73, v212
	s_waitcnt lgkmcnt(4)
	v_mfma_f32_32x32x16_bf16 v[16:31], v[136:139], v[232:235], v[16:31]
	v_exp_f32_e32 v76, v76
	v_exp_f32_e32 v77, v77
	v_add_f32_e32 v212, v74, v212
	v_add_f32_e32 v212, v75, v212
	v_mfma_f32_32x32x16_bf16 v[0:15], v[204:207], v[232:235], v[0:15]
	v_exp_f32_e32 v78, v78
	v_exp_f32_e32 v79, v79
	v_add_f32_e32 v212, v76, v212
	v_add_f32_e32 v212, v77, v212
	s_min_u32 s12, s34, 0x7f
	s_lshl_b32 s12, s12, 6
	s_sub_i32 s14, s12, s47
	s_sub_i32 s15, s14, 31
	s_cmpk_lt_i32 s15, 0x22f
	s_cselect_b32 s98, s100, s101
	s_cselect_b32 s15, 1, 0
	s_cmpk_gt_i32 s14, 0xfd92
	s_cselect_b32 s15, s15, 0
	s_cmp_lg_u32 s15, 0
	s_cbranch_scc1 .Lgather_o
	s_cmp_lg_u32 s99, s98
	s_cbranch_scc1 .Lz_upd_o

; #define FLAS __attribute__((address_space(3)))
; #define FA_SB() __builtin_amdgcn_sched_barrier(0)
; #define FA_EXP2(J, PX, R) do { const float e0_ = __builtin_amdgcn_exp2f(PX[R]), e1_ = __builtin_amdgcn_exp2f(PX[(R) + 1]); ps += e0_; ps += e1_; PWN[(J) >> 2][(J) & 3] = cvtpk(e0_, e1_); } while (0)
; __device__ __forceinline__ void attn_unit_a(FLAS unsigned char* lds, const Unit u) {
;     ...
;         u32x4 vr[3];
; #pragma unroll
;         for (int m = 0; m < 3; ++m) vr[m] = FA_VFRAG(m);
;     ...
;         kf[0] = FA_KF(2, 0); kf[1] = FA_KF(2, 1); FA_EXP2(9, pC1, 2); FA_SB();
;         pN0 = __builtin_amdgcn_mfma_f32_32x32x16_bf16(kf[2], qr[1], pN0, 0, 0, 0); FA_EXP2(10, pC1, 4); FA_SB();
;         pN1 = __builtin_amdgcn_mfma_f32_32x32x16_bf16(kf[3], qr[1], pN1, 0, 0, 0); kf[2] = FA_KF(3, 0); kf[3] = FA_KF(3, 1); FA_EXP2(11, pC1, 6); FA_SB();
;         pN0 = __builtin_amdgcn_mfma_f32_32x32x16_bf16(kf[0], qr[2], pN0, 0, 0, 0); FA_EXP2(12, pC1, 8); FA_SB();
;         pN1 = __builtin_amdgcn_mfma_f32_32x32x16_bf16(kf[1], qr[2], pN1, 0, 0, 0); FA_EXP2(13, pC1, 10); FA_SB();
;         pN0 = __builtin_amdgcn_mfma_f32_32x32x16_bf16(kf[2], qr[3], pN0, 0, 0, 0); FA_EXP2(14, pC1, 12); FA_SB();
;         pN1 = __builtin_amdgcn_mfma_f32_32x32x16_bf16(kf[3], qr[3], pN1, 0, 0, 0); FA_EXP2(15, pC1, 14); FA_SB();
;     ...
;         lsum += ps; cbC = cbN;
;         if (i + 2 < NT) { *(FLAS u32x4*)(lds + LA_K + (i & 1) * KBUF + kdst) = kreg;
; #pragma unroll
;             for (int j = 0; j < 2; ++j) { *(FLAS u32x2*)(lds + LA_V + ((i + 2) & 3) * VBUF + vdst + j * 64 * VPITCH) = (u32x2){vreg[j].x, vreg[j].y}; *(FLAS u32x2*)(lds + LA_V + ((i + 2) & 3) * VBUF + vdst + j * 64 * VPITCH + 16) = (u32x2){vreg[j].z, vreg[j].w}; } }
.Lk2_o:
	ds_read_b128 v[128:131], v249
	ds_read_b128 v[132:135], v249 offset:512
	v_mfma_f32_32x32x16_bf16 v[96:111], v[192:195], v[164:167], v[96:111]
	v_exp_f32_e32 v84, v84
	v_exp_f32_e32 v85, v85
	v_mfma_f32_32x32x16_bf16 v[112:127], v[188:191], v[164:167], v[112:127]
	ds_read_b128 v[136:139], v250
	ds_read_b128 v[140:143], v250 offset:512
	v_add_u32_e32 v204, s18, v245
	v_add_u32_e32 v205, 0x4000, v204
	v_add_u32_e32 v204, 0x6000, v204
	s_waitcnt vmcnt(2)
	ds_write_b128 v225, v[176:179] offset:8192
	s_waitcnt vmcnt(1)
	ds_write2_b64 v205, v[180:181], v[182:183] offset1:2
	s_waitcnt vmcnt(0)
	ds_write2_b64 v204, v[184:185], v[186:187] offset0:128 offset1:130
	v_exp_f32_e32 v86, v86
	v_exp_f32_e32 v87, v87
	s_add_i32 s12, s34, -1
	s_and_b32 s18, s12, 3
	s_mulk_i32 s18, 0x4800
	v_add_u32_e32 v200, s18, v251
	ds_read_b128 v[232:235], v200 offset:30208
	s_waitcnt lgkmcnt(6)
	v_mfma_f32_32x32x16_bf16 v[96:111], v[128:131], v[168:171], v[96:111]
	ds_read_b128 v[128:131], v200 offset:16384
	v_exp_f32_e32 v88, v88
	v_exp_f32_e32 v89, v89
	v_mfma_f32_32x32x16_bf16 v[112:127], v[132:135], v[168:171], v[112:127]
	ds_read_b128 v[132:135], v200 offset:20992
	v_exp_f32_e32 v90, v90
	v_exp_f32_e32 v91, v91
	s_waitcnt lgkmcnt(6)
	v_mfma_f32_32x32x16_bf16 v[96:111], v[136:139], v[172:175], v[96:111]
	ds_read_b128 v[136:139], v200 offset:25600
	v_exp_f32_e32 v92, v92
	v_exp_f32_e32 v93, v93
	v_mfma_f32_32x32x16_bf16 v[112:127], v[140:143], v[172:175], v[112:127]
	v_exp_f32_e32 v94, v94
	v_exp_f32_e32 v95, v95
